# front pass-2 tile split 1/2/3/5
# baseline (speedup 1.0000x reference)
.LBB0_155:
	s_or_b64 exec, exec, s[0:1]
	s_mov_b32 s100, 1
	s_lshr_b32 s0, s83, 6
	s_and_b32 s1, s83, 63
	s_movk_i32 s4, 1
	s_movk_i32 s5, 512
	s_cmp_eq_u32 s0, 1
	s_cselect_b32 s4, 2, s4
	s_cselect_b32 s5, 576, s5
	s_cmp_eq_u32 s0, 2
	s_cselect_b32 s4, 3, s4
	s_cselect_b32 s5, 704, s5
	s_cmp_eq_u32 s0, 3
	s_cselect_b32 s4, 5, s4
	s_cselect_b32 s5, 896, s5
	s_mul_i32 s6, s1, s4
	s_add_i32 s8, s5, s6
	s_add_i32 s10, s8, s4
	s_cmp_eq_u32 s4, 0
	s_cbranch_scc1 .Lp0_second_done
	s_mul_i32 s3, s62, 0x2080
	s_mov_b32 s33, s3
	s_branch .LBB0_34
